# adds batched loads in w_in transpose tile, 2x-unrolled sample-row GEMM loops with 32 loads in flight
# speedup vs baseline: 1.0060x; 1.0060x over previous
; #define MFMA32(a, b, c) __builtin_amdgcn_mfma_f32_32x32x16_bf16((a), (b), (c), 0, 0, 0)
; DI int TIDX() { int t = __builtin_amdgcn_workitem_id_x(); asm volatile("" : "+v"(t)); return t; }
; DI void wave_gemm32(f32x16& acc, const u16* A, int lda, const u16* Bt, int ldb, int K) {
;   const int lane = TIDX() & 63, r = lane & 31, hl = lane >> 5;
;   const u16* ap = A + (size_t)r * lda + hl * 8; const u16* bp = Bt + (size_t)r * ldb + hl * 8;
; #pragma unroll 8
;   for (int k = 0; k < K; k += 16) { bf16x8 a = *(const bf16x8*)(ap + k); bf16x8 b = *(const bf16x8*)(bp + k); acc = MFMA32(a, b, acc); }
; }
; DI void phase6(const Params& p, int l, unsigned char* smem) {
;     ...
;       for (int g = 0; g < 3; g++) {
;         f32x16 ay, ag;
; #pragma unroll
;         for (int i = 0; i < 16; i++) { ay[i] = 0.f; ag[i] = 0.f; }
;         wave_gemm32(ay, YG + ((size_t)g * NT + row0) * 512, 512, (const u16*)(p.ws + W_WBRT) + ((size_t)(l * 3 + g) * 1024 + n0) * 512, 512, 512);
;         wave_gemm32(ag, H + (size_t)row0 * 1024, 1024, WinT + (size_t)(5408 + g * 1024 + n0) * 1024, 1024, 1024);
.LBB0_954:
	global_load_dwordx4 v[64:67], v[18:19], off offset:-128
	global_load_dwordx4 v[68:71], v[16:17], off offset:-128
	global_load_dwordx4 v[72:75], v[18:19], off offset:-96
	global_load_dwordx4 v[76:79], v[16:17], off offset:-96
	global_load_dwordx4 v[80:83], v[18:19], off offset:-64
	global_load_dwordx4 v[90:93], v[16:17], off offset:-64
	global_load_dwordx4 v[96:99], v[18:19], off offset:-32
	global_load_dwordx4 v[100:103], v[16:17], off offset:-32
	global_load_dwordx4 v[104:107], v[18:19], off
	global_load_dwordx4 v[108:111], v[16:17], off
	global_load_dwordx4 v[112:115], v[18:19], off offset:32
	global_load_dwordx4 v[116:119], v[16:17], off offset:32
	global_load_dwordx4 v[120:123], v[18:19], off offset:64
	global_load_dwordx4 v[124:127], v[16:17], off offset:64
	global_load_dwordx4 v[128:131], v[18:19], off offset:96
	global_load_dwordx4 v[132:135], v[16:17], off offset:96
	global_load_dwordx4 v[136:139], v[18:19], off offset:128
	global_load_dwordx4 v[140:143], v[16:17], off offset:128
	global_load_dwordx4 v[144:147], v[18:19], off offset:160
	global_load_dwordx4 v[148:151], v[16:17], off offset:160
	global_load_dwordx4 v[152:155], v[18:19], off offset:192
	global_load_dwordx4 v[164:167], v[16:17], off offset:192
	global_load_dwordx4 v[168:171], v[18:19], off offset:224
	global_load_dwordx4 v[172:175], v[16:17], off offset:224
	global_load_dwordx4 v[176:179], v[18:19], off offset:256
	global_load_dwordx4 v[180:183], v[16:17], off offset:256
	global_load_dwordx4 v[190:193], v[18:19], off offset:288
	global_load_dwordx4 v[208:211], v[16:17], off offset:288
	global_load_dwordx4 v[212:215], v[18:19], off offset:320
	global_load_dwordx4 v[216:219], v[16:17], off offset:320
	global_load_dwordx4 v[20:23], v[18:19], off offset:352
	global_load_dwordx4 v[24:27], v[16:17], off offset:352
	s_addk_i32 s3, 0x100
	s_cmpk_lt_u32 s3, 0x1f0
	s_waitcnt vmcnt(30)
	v_mfma_f32_32x32x16_bf16 v[0:15], v[64:67], v[68:71], v[0:15]
	s_nop 1
	s_waitcnt vmcnt(28)
	v_mfma_f32_32x32x16_bf16 v[0:15], v[72:75], v[76:79], v[0:15]
	s_nop 1
	s_waitcnt vmcnt(26)
	v_mfma_f32_32x32x16_bf16 v[0:15], v[80:83], v[90:93], v[0:15]
	s_nop 1
	s_waitcnt vmcnt(24)
	v_mfma_f32_32x32x16_bf16 v[0:15], v[96:99], v[100:103], v[0:15]
	s_nop 1
	s_waitcnt vmcnt(22)
	v_mfma_f32_32x32x16_bf16 v[0:15], v[104:107], v[108:111], v[0:15]
	s_nop 1
	s_waitcnt vmcnt(20)
	v_mfma_f32_32x32x16_bf16 v[0:15], v[112:115], v[116:119], v[0:15]
	s_nop 1
	s_waitcnt vmcnt(18)
	v_mfma_f32_32x32x16_bf16 v[0:15], v[120:123], v[124:127], v[0:15]
	s_nop 1
	s_waitcnt vmcnt(16)
	v_mfma_f32_32x32x16_bf16 v[0:15], v[128:131], v[132:135], v[0:15]
	s_nop 1
	s_waitcnt vmcnt(14)
	v_mfma_f32_32x32x16_bf16 v[0:15], v[136:139], v[140:143], v[0:15]
	s_nop 1
	s_waitcnt vmcnt(12)
	v_mfma_f32_32x32x16_bf16 v[0:15], v[144:147], v[148:151], v[0:15]
	s_nop 1
	s_waitcnt vmcnt(10)
	v_mfma_f32_32x32x16_bf16 v[0:15], v[152:155], v[164:167], v[0:15]
	s_nop 1
	s_waitcnt vmcnt(8)
	v_mfma_f32_32x32x16_bf16 v[0:15], v[168:171], v[172:175], v[0:15]
	s_nop 1
	s_waitcnt vmcnt(6)
	v_mfma_f32_32x32x16_bf16 v[0:15], v[176:179], v[180:183], v[0:15]
	s_nop 1
	s_waitcnt vmcnt(4)
	v_mfma_f32_32x32x16_bf16 v[0:15], v[190:193], v[208:211], v[0:15]
	s_nop 1
	s_waitcnt vmcnt(2)
	v_mfma_f32_32x32x16_bf16 v[0:15], v[212:215], v[216:219], v[0:15]
	s_nop 1
	v_lshl_add_u64 v[16:17], v[16:17], 0, s[58:59]
	v_lshl_add_u64 v[16:17], v[16:17], 0, s[58:59]
	v_lshl_add_u64 v[18:19], v[18:19], 0, s[58:59]
	v_lshl_add_u64 v[18:19], v[18:19], 0, s[58:59]
	s_waitcnt vmcnt(0)
	v_mfma_f32_32x32x16_bf16 v[0:15], v[20:23], v[24:27], v[0:15]
	s_cbranch_scc1 .LBB0_954
	v_mov_b32_e32 v18, v160
	v_ashrrev_i32_e32 v53, 31, v52
	v_lshrrev_b32_e32 v19, 1, v18
	v_and_b32_e32 v18, 31, v18
	v_lshlrev_b64 v[16:17], 11, v[52:53]
	v_and_b32_e32 v162, 16, v19
	v_lshlrev_b32_e32 v18, 11, v18
	v_mov_b32_e32 v19, v163
	v_lshl_add_u64 v[16:17], v[16:17], 0, v[18:19]
	v_lshl_add_u64 v[56:57], s[76:77], 0, v[16:17]
	v_mov_b32_e32 v16, 0
	v_lshl_add_u64 v[58:59], v[54:55], 0, v[18:19]
	s_mov_b32 s3, -16
	v_mov_b32_e32 v17, v16
	v_mov_b32_e32 v18, v16
	v_mov_b32_e32 v19, v16
	v_mov_b32_e32 v20, v16
	v_mov_b32_e32 v21, v16
	v_mov_b32_e32 v22, v16
	v_mov_b32_e32 v23, v16
	v_mov_b32_e32 v24, v16
	v_mov_b32_e32 v25, v16
	v_mov_b32_e32 v26, v16
	v_mov_b32_e32 v27, v16
	v_mov_b32_e32 v28, v16
	v_mov_b32_e32 v29, v16
	v_mov_b32_e32 v30, v16
	v_mov_b32_e32 v31, v16
; #define MFMA32(a, b, c) __builtin_amdgcn_mfma_f32_32x32x16_bf16((a), (b), (c), 0, 0, 0)
; DI int TIDX() { int t = __builtin_amdgcn_workitem_id_x(); asm volatile("" : "+v"(t)); return t; }
; DI void wave_gemm32(f32x16& acc, const u16* A, int lda, const u16* Bt, int ldb, int K) {
;   const int lane = TIDX() & 63, r = lane & 31, hl = lane >> 5;
;   const u16* ap = A + (size_t)r * lda + hl * 8; const u16* bp = Bt + (size_t)r * ldb + hl * 8;
; #pragma unroll 8
;   for (int k = 0; k < K; k += 16) { bf16x8 a = *(const bf16x8*)(ap + k); bf16x8 b = *(const bf16x8*)(bp + k); acc = MFMA32(a, b, acc); }
; }
; DI void phase6(const Params& p, int l, unsigned char* smem) {
;     ...
;         wave_gemm32(ag, H + (size_t)row0 * 1024, 1024, WinT + (size_t)(5408 + g * 1024 + n0) * 1024, 1024, 1024);
.LBB0_956:
	v_lshl_add_u64 v[72:73], v[58:59], 0, v[162:163]
	global_load_dwordx4 v[76:79], v[72:73], off offset:-128
	v_lshl_add_u64 v[74:75], v[56:57], 0, v[162:163]
	global_load_dwordx4 v[80:83], v[74:75], off
	global_load_dwordx4 v[90:93], v[72:73], off offset:-96
	global_load_dwordx4 v[96:99], v[74:75], off offset:32
	global_load_dwordx4 v[100:103], v[72:73], off offset:-64
	global_load_dwordx4 v[104:107], v[74:75], off offset:64
	global_load_dwordx4 v[108:111], v[72:73], off offset:-32
	global_load_dwordx4 v[112:115], v[74:75], off offset:96
	global_load_dwordx4 v[116:119], v[72:73], off
	global_load_dwordx4 v[120:123], v[74:75], off offset:128
	global_load_dwordx4 v[124:127], v[72:73], off offset:32
	global_load_dwordx4 v[128:131], v[74:75], off offset:160
	global_load_dwordx4 v[132:135], v[72:73], off offset:64
	global_load_dwordx4 v[136:139], v[74:75], off offset:192
	global_load_dwordx4 v[140:143], v[72:73], off offset:96
	global_load_dwordx4 v[144:147], v[74:75], off offset:224
	global_load_dwordx4 v[148:151], v[72:73], off offset:128
	global_load_dwordx4 v[152:155], v[74:75], off offset:256
	global_load_dwordx4 v[164:167], v[72:73], off offset:160
	global_load_dwordx4 v[168:171], v[74:75], off offset:288
	global_load_dwordx4 v[172:175], v[72:73], off offset:192
	global_load_dwordx4 v[176:179], v[74:75], off offset:320
	global_load_dwordx4 v[180:183], v[72:73], off offset:224
	global_load_dwordx4 v[190:193], v[74:75], off offset:352
	global_load_dwordx4 v[208:211], v[72:73], off offset:256
	global_load_dwordx4 v[212:215], v[74:75], off offset:384
	global_load_dwordx4 v[216:219], v[72:73], off offset:288
	global_load_dwordx4 v[220:223], v[74:75], off offset:416
	global_load_dwordx4 v[224:227], v[72:73], off offset:320
	global_load_dwordx4 v[228:231], v[74:75], off offset:448
	global_load_dwordx4 v[64:67], v[72:73], off offset:352
	global_load_dwordx4 v[68:71], v[74:75], off offset:480
	s_addk_i32 s3, 0x100
	v_lshl_add_u64 v[56:57], v[56:57], 0, s[58:59]
	v_lshl_add_u64 v[58:59], v[58:59], 0, s[58:59]
	v_lshl_add_u64 v[56:57], v[56:57], 0, s[58:59]
	v_lshl_add_u64 v[58:59], v[58:59], 0, s[58:59]
	s_cmpk_lt_u32 s3, 0x3f0
	s_nop 1
	s_waitcnt vmcnt(30)
	v_mfma_f32_32x32x16_bf16 v[16:31], v[76:79], v[80:83], v[16:31]
	s_nop 1
	s_waitcnt vmcnt(28)
	v_mfma_f32_32x32x16_bf16 v[16:31], v[90:93], v[96:99], v[16:31]
	s_nop 1
	s_waitcnt vmcnt(26)
	v_mfma_f32_32x32x16_bf16 v[16:31], v[100:103], v[104:107], v[16:31]
	s_nop 1
	s_waitcnt vmcnt(24)
	v_mfma_f32_32x32x16_bf16 v[16:31], v[108:111], v[112:115], v[16:31]
	s_nop 1
	s_waitcnt vmcnt(22)
	v_mfma_f32_32x32x16_bf16 v[16:31], v[116:119], v[120:123], v[16:31]
	s_nop 1
	s_waitcnt vmcnt(20)
	v_mfma_f32_32x32x16_bf16 v[16:31], v[124:127], v[128:131], v[16:31]
	s_nop 1
	s_waitcnt vmcnt(18)
	v_mfma_f32_32x32x16_bf16 v[16:31], v[132:135], v[136:139], v[16:31]
	s_nop 1
	s_waitcnt vmcnt(16)
	v_mfma_f32_32x32x16_bf16 v[16:31], v[140:143], v[144:147], v[16:31]
	s_nop 1
	s_waitcnt vmcnt(14)
	v_mfma_f32_32x32x16_bf16 v[16:31], v[148:151], v[152:155], v[16:31]
	s_nop 1
	s_waitcnt vmcnt(12)
	v_mfma_f32_32x32x16_bf16 v[16:31], v[164:167], v[168:171], v[16:31]
	s_nop 1
	s_waitcnt vmcnt(10)
	v_mfma_f32_32x32x16_bf16 v[16:31], v[172:175], v[176:179], v[16:31]
	s_nop 1
	s_waitcnt vmcnt(8)
	v_mfma_f32_32x32x16_bf16 v[16:31], v[180:183], v[190:193], v[16:31]
	s_nop 1
	s_waitcnt vmcnt(6)
	v_mfma_f32_32x32x16_bf16 v[16:31], v[208:211], v[212:215], v[16:31]
	s_nop 1
	s_waitcnt vmcnt(4)
	v_mfma_f32_32x32x16_bf16 v[16:31], v[216:219], v[220:223], v[16:31]
	s_nop 1
	s_waitcnt vmcnt(2)
	v_mfma_f32_32x32x16_bf16 v[16:31], v[224:227], v[228:231], v[16:31]
	s_nop 1
	s_waitcnt vmcnt(0)
	v_mfma_f32_32x32x16_bf16 v[16:31], v[64:67], v[68:71], v[16:31]
	s_cbranch_scc1 .LBB0_956
; DI float sigmoidf_(float x) { return frcp(1.f + __expf(-x)); }
; DI int crow(int i, int hl) { return (i & 3) + 8 * (i >> 2) + 4 * hl; }
; DI void phase6(const Params& p, int l, unsigned char* smem) {
;     ...
; #pragma unroll
;         for (int i = 0; i < 16; i++) mm[i] += sigmoidf_(ag[i]) * ay[i];
;       }
; #pragma unroll
;       for (int i = 0; i < 16; i++) MG[(size_t)(row0 + crow(i, hl)) * 1024 + n0 + r] = f2bf(mm[i]);
	s_nop 10
	v_mul_f32_e32 v16, 0xbfb8aa3b, v16
	v_mul_f32_e32 v17, 0xbfb8aa3b, v17
	v_exp_f32_e32 v16, v16
	v_exp_f32_e32 v17, v17
	s_add_i32 s12, s12, 1
	s_add_i32 s2, s2, 1
	v_add_f32_e32 v16, 1.0, v16
	v_add_f32_e32 v17, 1.0, v17
	v_rcp_f32_e32 v16, v16
	v_rcp_f32_e32 v17, v17
	s_mov_b64 s[14:15], 0x1020000
	v_lshl_add_u64 v[50:51], v[50:51], 0, s[14:15]
	v_add_u32_e32 v52, 0x400, v52
	v_pk_fma_f32 v[46:47], v[0:1], v[16:17], v[46:47]
	v_mul_f32_e32 v0, 0xbfb8aa3b, v18
	v_mul_f32_e32 v1, 0xbfb8aa3b, v19
	v_exp_f32_e32 v0, v0
	v_exp_f32_e32 v1, v1
	s_cmp_eq_u32 s12, 3
	v_add_f32_e32 v0, 1.0, v0
	v_add_f32_e32 v1, 1.0, v1
	v_rcp_f32_e32 v0, v0
	v_rcp_f32_e32 v1, v1
	s_nop 0
	v_pk_fma_f32 v[44:45], v[2:3], v[0:1], v[44:45]
	v_mul_f32_e32 v0, 0xbfb8aa3b, v20
	v_mul_f32_e32 v1, 0xbfb8aa3b, v21
	v_exp_f32_e32 v0, v0
	v_exp_f32_e32 v1, v1
	v_add_f32_e32 v0, 1.0, v0
	v_add_f32_e32 v1, 1.0, v1
	v_rcp_f32_e32 v0, v0
	v_rcp_f32_e32 v1, v1
	s_nop 0
	v_pk_fma_f32 v[42:43], v[4:5], v[0:1], v[42:43]
	v_mul_f32_e32 v0, 0xbfb8aa3b, v22
	v_mul_f32_e32 v1, 0xbfb8aa3b, v23
	v_exp_f32_e32 v0, v0
	v_exp_f32_e32 v1, v1
	v_add_f32_e32 v0, 1.0, v0
	v_add_f32_e32 v1, 1.0, v1
	v_rcp_f32_e32 v0, v0
	v_rcp_f32_e32 v1, v1
	s_nop 0
	v_pk_fma_f32 v[40:41], v[6:7], v[0:1], v[40:41]
	v_mul_f32_e32 v0, 0xbfb8aa3b, v24
	v_mul_f32_e32 v1, 0xbfb8aa3b, v25
	v_exp_f32_e32 v0, v0
	v_exp_f32_e32 v1, v1
	v_add_f32_e32 v0, 1.0, v0
	v_add_f32_e32 v1, 1.0, v1
	v_rcp_f32_e32 v0, v0
	v_rcp_f32_e32 v1, v1
	s_nop 0
	v_pk_fma_f32 v[38:39], v[8:9], v[0:1], v[38:39]
	v_mul_f32_e32 v0, 0xbfb8aa3b, v26
	v_mul_f32_e32 v1, 0xbfb8aa3b, v27
	v_exp_f32_e32 v0, v0
	v_exp_f32_e32 v1, v1
	v_add_f32_e32 v0, 1.0, v0
	v_add_f32_e32 v1, 1.0, v1
	v_rcp_f32_e32 v0, v0
	v_rcp_f32_e32 v1, v1
	s_nop 0
	v_pk_fma_f32 v[36:37], v[10:11], v[0:1], v[36:37]
	v_mul_f32_e32 v0, 0xbfb8aa3b, v28
	v_mul_f32_e32 v1, 0xbfb8aa3b, v29
	v_exp_f32_e32 v0, v0
	v_exp_f32_e32 v1, v1
	v_add_f32_e32 v0, 1.0, v0
	v_add_f32_e32 v1, 1.0, v1
	v_rcp_f32_e32 v0, v0
	v_rcp_f32_e32 v1, v1
	s_nop 0
	v_pk_fma_f32 v[34:35], v[12:13], v[0:1], v[34:35]
	v_mul_f32_e32 v0, 0xbfb8aa3b, v30
	v_mul_f32_e32 v1, 0xbfb8aa3b, v31
	v_exp_f32_e32 v0, v0
	v_exp_f32_e32 v1, v1
	v_add_f32_e32 v0, 1.0, v0
	v_add_f32_e32 v1, 1.0, v1
	v_rcp_f32_e32 v0, v0
	v_rcp_f32_e32 v1, v1
	s_nop 0
	v_pk_fma_f32 v[32:33], v[14:15], v[0:1], v[32:33]
	s_cbranch_scc0 .LBB0_953
	v_lshrrev_b32_e32 v2, 3, v60
	v_lshlrev_b32_e32 v0, 5, v61
	v_lshl_add_u32 v1, s36, 5, v62
	v_and_b32_e32 v2, 4, v2
	s_movk_i32 s2, 0x60
	v_and_or_b32 v2, v0, s2, v2
	v_and_b32_e32 v0, 0xffffffe0, v1
	v_ashrrev_i32_e32 v1, 31, v0
	v_and_b32_e32 v3, 31, v60
	v_lshl_add_u64 v[0:1], v[0:1], 1, s[80:81]
	v_lshlrev_b32_e32 v162, 1, v3
	v_bfrev_b32_e32 v4, 64
	v_lshl_add_u64 v[0:1], v[0:1], 0, v[162:163]
	v_lshl_or_b32 v162, v2, 11, v4
	v_lshl_add_u64 v[0:1], v[0:1], 0, v[162:163]
	v_cvt_pk_bf16_f32 v2, v47, s0
	v_cvt_pk_bf16_f32 v3, v46, s0
	global_store_short v[0:1], v2, off offset:2048
	v_add_co_u32_e32 v2, vcc, s60, v0
	global_store_short v[0:1], v3, off
	v_cvt_pk_bf16_f32 v4, v44, s0
	v_addc_co_u32_e32 v3, vcc, 0, v1, vcc
	global_store_short v[2:3], v4, off
	v_cvt_pk_bf16_f32 v4, v45, s0
	global_store_short v[2:3], v4, off offset:2048
	v_add_co_u32_e32 v2, vcc, s50, v0
	s_movk_i32 s2, 0x5000
	s_nop 0
	v_addc_co_u32_e32 v3, vcc, 0, v1, vcc
	v_add_co_u32_e32 v4, vcc, s2, v0
	v_cvt_pk_bf16_f32 v6, v42, s0
	s_nop 0
	v_addc_co_u32_e32 v5, vcc, 0, v1, vcc
	global_store_short v[4:5], v6, off offset:-4096
	v_cvt_pk_bf16_f32 v6, v43, s0
	global_store_short v[2:3], v6, off offset:2048
	v_cvt_pk_bf16_f32 v2, v40, s0
	global_store_short v[4:5], v2, off
	v_cvt_pk_bf16_f32 v2, v41, s0
	s_mov_b32 s2, 0x8000
	global_store_short v[4:5], v2, off offset:2048
	v_add_co_u32_e32 v2, vcc, s2, v0
	s_mov_b32 s2, 0x9000
	s_nop 0
	v_addc_co_u32_e32 v3, vcc, 0, v1, vcc
	v_add_co_u32_e32 v4, vcc, s2, v0
	v_cvt_pk_bf16_f32 v6, v38, s0
	s_nop 0
	v_addc_co_u32_e32 v5, vcc, 0, v1, vcc
	global_store_short v[4:5], v6, off offset:-4096
	v_cvt_pk_bf16_f32 v6, v39, s0
	global_store_short v[2:3], v6, off offset:2048
	v_cvt_pk_bf16_f32 v2, v36, s0
	global_store_short v[4:5], v2, off
	v_cvt_pk_bf16_f32 v2, v37, s0
	global_store_short v[4:5], v2, off offset:2048
	v_add_co_u32_e32 v2, vcc, 0xc000, v0
	v_cvt_pk_bf16_f32 v4, v34, s0
	s_nop 0
	v_addc_co_u32_e32 v3, vcc, 0, v1, vcc
	global_store_short v[2:3], v4, off
	v_cvt_pk_bf16_f32 v4, v35, s0
	v_add_co_u32_e32 v0, vcc, 0xd000, v0
	global_store_short v[2:3], v4, off offset:2048
	v_cvt_pk_bf16_f32 v2, v32, s0
	v_addc_co_u32_e32 v1, vcc, 0, v1, vcc
	global_store_short v[0:1], v2, off
	v_cvt_pk_bf16_f32 v2, v33, s0
	global_store_short v[0:1], v2, off offset:2048
	s_branch .LBB0_942

; #define MFMA32(a, b, c) __builtin_amdgcn_mfma_f32_32x32x16_bf16((a), (b), (c), 0, 0, 0)
; DI int TIDX() { int t = __builtin_amdgcn_workitem_id_x(); asm volatile("" : "+v"(t)); return t; }
; DI int crow(int i, int hl) { return (i & 3) + 8 * (i >> 2) + 4 * hl; }
; DI void wave_gemm32(f32x16& acc, const u16* A, int lda, const u16* Bt, int ldb, int K) {
;   const int lane = TIDX() & 63, r = lane & 31, hl = lane >> 5;
;   const u16* ap = A + (size_t)r * lda + hl * 8; const u16* bp = Bt + (size_t)r * ldb + hl * 8;
; #pragma unroll 8
;   for (int k = 0; k < K; k += 16) { bf16x8 a = *(const bf16x8*)(ap + k); bf16x8 b = *(const bf16x8*)(bp + k); acc = MFMA32(a, b, acc); }
; }
; DI void phase7(const Params& p, int l, unsigned char* smem) {
;     ...
;       wave_gemm32(a, MG + (size_t)row0 * 1024, 1024, (const u16*)(p.ws + W_WOUTT) + ((size_t)l * 1024 + n0) * 1024, 1024, 1024);
; #pragma unroll
;       for (int i = 0; i < 16; i++) {
;         const int row = row0 + crow(i, hl), col = n0 + r;
;         float xo = xrow_ptr(p, l, row)[col];
;         float gt = mod[(l * 10 + bidx_of(row)) * 3072 + 2048 + col];
;         p.out[(size_t)row * D + col] = xo + gt * a[i];
;       }
.LBB0_1520:
	global_load_dwordx4 v[32:35], v[18:19], off offset:-128
	global_load_dwordx4 v[36:39], v[16:17], off offset:-128
	global_load_dwordx4 v[40:43], v[18:19], off offset:-96
	global_load_dwordx4 v[44:47], v[16:17], off offset:-96
	global_load_dwordx4 v[50:53], v[18:19], off offset:-64
	global_load_dwordx4 v[58:61], v[16:17], off offset:-64
	global_load_dwordx4 v[62:65], v[18:19], off offset:-32
	global_load_dwordx4 v[66:69], v[16:17], off offset:-32
	global_load_dwordx4 v[70:73], v[18:19], off
	global_load_dwordx4 v[74:77], v[16:17], off
	global_load_dwordx4 v[78:81], v[18:19], off offset:32
	global_load_dwordx4 v[82:85], v[16:17], off offset:32
	global_load_dwordx4 v[90:93], v[18:19], off offset:64
	global_load_dwordx4 v[96:99], v[16:17], off offset:64
	global_load_dwordx4 v[100:103], v[18:19], off offset:96
	global_load_dwordx4 v[104:107], v[16:17], off offset:96
	global_load_dwordx4 v[108:111], v[18:19], off offset:128
	global_load_dwordx4 v[112:115], v[16:17], off offset:128
	global_load_dwordx4 v[116:119], v[18:19], off offset:160
	global_load_dwordx4 v[120:123], v[16:17], off offset:160
	global_load_dwordx4 v[124:127], v[18:19], off offset:192
	global_load_dwordx4 v[128:131], v[16:17], off offset:192
	global_load_dwordx4 v[132:135], v[18:19], off offset:224
	global_load_dwordx4 v[136:139], v[16:17], off offset:224
	global_load_dwordx4 v[140:143], v[18:19], off offset:256
	global_load_dwordx4 v[144:147], v[16:17], off offset:256
	global_load_dwordx4 v[148:151], v[18:19], off offset:288
	global_load_dwordx4 v[152:155], v[16:17], off offset:288
	global_load_dwordx4 v[164:167], v[18:19], off offset:320
	global_load_dwordx4 v[168:171], v[16:17], off offset:320
	global_load_dwordx4 v[24:27], v[18:19], off offset:352
	global_load_dwordx4 v[28:31], v[16:17], off offset:352
	s_addk_i32 s2, 0x100
	s_cmpk_lt_u32 s2, 0x3f0
	s_waitcnt vmcnt(30)
	v_mfma_f32_32x32x16_bf16 v[0:15], v[32:35], v[36:39], v[0:15]
	s_nop 1
	s_waitcnt vmcnt(28)
	v_mfma_f32_32x32x16_bf16 v[0:15], v[40:43], v[44:47], v[0:15]
	s_nop 1
	s_waitcnt vmcnt(26)
	v_mfma_f32_32x32x16_bf16 v[0:15], v[50:53], v[58:61], v[0:15]
	s_nop 1
	s_waitcnt vmcnt(24)
	v_mfma_f32_32x32x16_bf16 v[0:15], v[62:65], v[66:69], v[0:15]
	s_nop 1
	s_waitcnt vmcnt(22)
	v_mfma_f32_32x32x16_bf16 v[0:15], v[70:73], v[74:77], v[0:15]
	s_nop 1
	s_waitcnt vmcnt(20)
	v_mfma_f32_32x32x16_bf16 v[0:15], v[78:81], v[82:85], v[0:15]
	s_nop 1
	s_waitcnt vmcnt(18)
	v_mfma_f32_32x32x16_bf16 v[0:15], v[90:93], v[96:99], v[0:15]
	s_nop 1
	s_waitcnt vmcnt(16)
	v_mfma_f32_32x32x16_bf16 v[0:15], v[100:103], v[104:107], v[0:15]
	s_nop 1
	s_waitcnt vmcnt(14)
	v_mfma_f32_32x32x16_bf16 v[0:15], v[108:111], v[112:115], v[0:15]
	s_nop 1
	s_waitcnt vmcnt(12)
	v_mfma_f32_32x32x16_bf16 v[0:15], v[116:119], v[120:123], v[0:15]
	s_nop 1
	s_waitcnt vmcnt(10)
	v_mfma_f32_32x32x16_bf16 v[0:15], v[124:127], v[128:131], v[0:15]
	s_nop 1
	s_waitcnt vmcnt(8)
	v_mfma_f32_32x32x16_bf16 v[0:15], v[132:135], v[136:139], v[0:15]
	s_nop 1
	s_waitcnt vmcnt(6)
	v_mfma_f32_32x32x16_bf16 v[0:15], v[140:143], v[144:147], v[0:15]
	s_nop 1
	s_waitcnt vmcnt(4)
	v_mfma_f32_32x32x16_bf16 v[0:15], v[148:151], v[152:155], v[0:15]
	s_nop 1
	s_waitcnt vmcnt(2)
	v_mfma_f32_32x32x16_bf16 v[0:15], v[164:167], v[168:171], v[0:15]
	s_nop 1
	v_lshl_add_u64 v[16:17], v[16:17], 0, s[58:59]
	v_lshl_add_u64 v[16:17], v[16:17], 0, s[58:59]
	v_lshl_add_u64 v[18:19], v[18:19], 0, s[58:59]
	v_lshl_add_u64 v[18:19], v[18:19], 0, s[58:59]
	s_waitcnt vmcnt(0)
	v_mfma_f32_32x32x16_bf16 v[0:15], v[24:27], v[28:31], v[0:15]
	s_cbranch_scc1 .LBB0_1520
	v_lshlrev_b32_e32 v16, 5, v22
	v_and_b32_e32 v26, 0x60, v16
	v_lshl_add_u32 v16, s95, 5, v21
	s_movk_i32 s2, 0xffe0
	v_bfi_b32 v16, s2, v16, v20
	v_readlane_b32 s2, v254, 41
	s_add_u32 s2, s0, s2
	s_addc_u32 s3, s1, 0
	s_load_dwordx2 s[2:3], s[2:3], 0x0
	v_lshrrev_b32_e32 v17, 3, v20
	v_and_or_b32 v21, v17, 4, v26
	v_ashrrev_i32_e32 v17, 31, v16
	v_lshlrev_b64 v[22:23], 2, v[16:17]
	s_waitcnt lgkmcnt(0)
	v_lshl_add_u64 v[18:19], s[2:3], 0, v[22:23]
	v_readlane_b32 s2, v254, 37
	v_readlane_b32 s3, v254, 38
	v_lshlrev_b32_e32 v21, 12, v21
	v_add_u32_e32 v20, 0x800, v16
	v_lshl_add_u64 v[16:17], s[2:3], 0, v[22:23]
	v_or_b32_e32 v22, 0x4000000, v21
	v_cndmask_b32_e64 v162, v21, v22, s[4:5]
	v_lshrrev_b32_e32 v28, 4, v26
	v_readlane_b32 s6, v254, 39
	v_lshl_add_u64 v[24:25], v[18:19], 0, v[162:163]
	global_load_dword v27, v[24:25], off
	v_add_u32_e32 v23, s6, v28
	v_mad_u64_u32 v[24:25], s[2:3], v23, s74, v[20:21]
	v_ashrrev_i32_e32 v25, 31, v24
	v_lshl_add_u64 v[24:25], v[24:25], 2, s[78:79]
	global_load_dword v23, v[24:25], off
	v_readlane_b32 s2, v254, 45
	s_waitcnt vmcnt(0)
	v_fmac_f32_e32 v27, v0, v23
	v_mov_b32_e32 v23, v163
	v_lshl_add_u64 v[22:23], v[16:17], 0, v[22:23]
	global_store_dword v[22:23], v27, off
	v_or_b32_e32 v0, 0x4001000, v21
	v_or_b32_e32 v22, 0x1000, v21
	v_cndmask_b32_e64 v162, v22, v0, s[4:5]
	v_lshl_add_u64 v[22:23], v[18:19], 0, v[162:163]
	global_load_dword v22, v[22:23], off
	s_nop 0
	global_load_dword v23, v[24:25], off
	s_waitcnt vmcnt(0)
	v_fmac_f32_e32 v22, v1, v23
	v_mov_b32_e32 v1, v163
	v_lshl_add_u64 v[0:1], v[16:17], 0, v[0:1]
	global_store_dword v[0:1], v22, off
	v_or_b32_e32 v0, 0x4002000, v21
	v_or_b32_e32 v1, 0x2000, v21
	v_cndmask_b32_e64 v162, v1, v0, s[4:5]
	v_lshl_add_u64 v[22:23], v[18:19], 0, v[162:163]
	global_load_dword v22, v[22:23], off
	s_nop 0
	global_load_dword v1, v[24:25], off
	s_waitcnt vmcnt(0)
; DI int crow(int i, int hl) { return (i & 3) + 8 * (i >> 2) + 4 * hl; }
; DI void phase7(const Params& p, int l, unsigned char* smem) {
;     ...
; #pragma unroll
;       for (int i = 0; i < 16; i++) {
;         const int row = row0 + crow(i, hl), col = n0 + r;
;         float xo = xrow_ptr(p, l, row)[col];
;         float gt = mod[(l * 10 + bidx_of(row)) * 3072 + 2048 + col];
;         p.out[(size_t)row * D + col] = xo + gt * a[i];
;       }
	v_fmac_f32_e32 v22, v2, v1
	v_mov_b32_e32 v1, v163
	v_lshl_add_u64 v[0:1], v[16:17], 0, v[0:1]
	global_store_dword v[0:1], v22, off
	v_or_b32_e32 v0, 0x4003000, v21
	v_or_b32_e32 v1, 0x3000, v21
	v_cndmask_b32_e64 v162, v1, v0, s[4:5]
	v_lshl_add_u64 v[22:23], v[18:19], 0, v[162:163]
	global_load_dword v2, v[22:23], off
	global_load_dword v1, v[24:25], off
	s_waitcnt vmcnt(0)
	v_fmac_f32_e32 v2, v3, v1
	v_mov_b32_e32 v1, v163
	v_lshl_add_u64 v[0:1], v[16:17], 0, v[0:1]
	global_store_dword v[0:1], v2, off
	v_or_b32_e32 v0, 0x4008000, v21
	v_or_b32_e32 v1, 0x8000, v21
	v_cndmask_b32_e64 v162, v1, v0, s[4:5]
	v_lshl_add_u64 v[2:3], v[18:19], 0, v[162:163]
	global_load_dword v2, v[2:3], off
	s_nop 0
	global_load_dword v1, v[24:25], off
	s_waitcnt vmcnt(0)
	v_fmac_f32_e32 v2, v4, v1
	v_mov_b32_e32 v1, v163
	v_lshl_add_u64 v[0:1], v[16:17], 0, v[0:1]
	global_store_dword v[0:1], v2, off
	v_or_b32_e32 v0, 0x4009000, v21
	v_or_b32_e32 v1, 0x9000, v21
	v_cndmask_b32_e64 v162, v1, v0, s[4:5]
	v_lshl_add_u64 v[2:3], v[18:19], 0, v[162:163]
	global_load_dword v2, v[2:3], off
	s_nop 0
	global_load_dword v1, v[24:25], off
	s_waitcnt vmcnt(0)
	v_fmac_f32_e32 v2, v5, v1
	v_mov_b32_e32 v1, v163
	v_lshl_add_u64 v[0:1], v[16:17], 0, v[0:1]
	global_store_dword v[0:1], v2, off
	v_or_b32_e32 v0, 0x400a000, v21
	v_or_b32_e32 v1, 0xa000, v21
	v_cndmask_b32_e64 v162, v1, v0, s[4:5]
	v_lshl_add_u64 v[2:3], v[18:19], 0, v[162:163]
	global_load_dword v2, v[2:3], off
	s_nop 0
	global_load_dword v1, v[24:25], off
	s_waitcnt vmcnt(0)
	v_fmac_f32_e32 v2, v6, v1
	v_mov_b32_e32 v1, v163
	v_lshl_add_u64 v[0:1], v[16:17], 0, v[0:1]
	global_store_dword v[0:1], v2, off
	v_or_b32_e32 v0, 0x400b000, v21
	v_or_b32_e32 v1, 0xb000, v21
	v_cndmask_b32_e64 v162, v1, v0, s[4:5]
	v_lshl_add_u64 v[2:3], v[18:19], 0, v[162:163]
	global_load_dword v2, v[2:3], off
	s_nop 0
	global_load_dword v1, v[24:25], off
	s_waitcnt vmcnt(0)
	v_fmac_f32_e32 v2, v7, v1
	v_mov_b32_e32 v1, v163
	v_lshl_add_u64 v[0:1], v[16:17], 0, v[0:1]
	global_store_dword v[0:1], v2, off
	v_or_b32_e32 v0, 0x4010000, v21
	v_or_b32_e32 v1, 0x10000, v21
	v_cndmask_b32_e64 v162, v1, v0, s[4:5]
	v_lshl_add_u64 v[2:3], v[18:19], 0, v[162:163]
	v_add_u32_e32 v1, s2, v28
	global_load_dword v4, v[2:3], off
	v_mad_u64_u32 v[2:3], s[2:3], v1, s74, v[20:21]
	v_ashrrev_i32_e32 v3, 31, v2
	v_lshl_add_u64 v[2:3], v[2:3], 2, s[78:79]
	global_load_dword v1, v[2:3], off
	s_waitcnt vmcnt(0)
	v_fmac_f32_e32 v4, v8, v1
	v_mov_b32_e32 v1, v163
	v_lshl_add_u64 v[0:1], v[16:17], 0, v[0:1]
	global_store_dword v[0:1], v4, off
	v_or_b32_e32 v0, 0x4011000, v21
	v_or_b32_e32 v1, 0x11000, v21
	v_cndmask_b32_e64 v162, v1, v0, s[4:5]
	v_or_b32_e32 v1, 16, v26
	v_lshrrev_b32_e32 v1, 4, v1
	v_lshl_add_u64 v[4:5], v[18:19], 0, v[162:163]
	v_add_u32_e32 v1, s6, v1
	global_load_dword v6, v[4:5], off
	v_mad_u64_u32 v[4:5], s[2:3], v1, s74, v[20:21]
	v_ashrrev_i32_e32 v5, 31, v4
	v_lshl_add_u64 v[4:5], v[4:5], 2, s[78:79]
	global_load_dword v1, v[4:5], off
	s_waitcnt vmcnt(0)
	v_fmac_f32_e32 v6, v9, v1
	v_mov_b32_e32 v1, v163
	v_lshl_add_u64 v[0:1], v[16:17], 0, v[0:1]
	global_store_dword v[0:1], v6, off
	v_or_b32_e32 v0, 0x4012000, v21
	v_or_b32_e32 v1, 0x12000, v21
	v_cndmask_b32_e64 v162, v1, v0, s[4:5]
	v_lshl_add_u64 v[6:7], v[18:19], 0, v[162:163]
	global_load_dword v6, v[6:7], off
	s_nop 0
	global_load_dword v1, v[4:5], off
	s_waitcnt vmcnt(0)
	v_fmac_f32_e32 v6, v10, v1
	v_mov_b32_e32 v1, v163
	v_lshl_add_u64 v[0:1], v[16:17], 0, v[0:1]
	global_store_dword v[0:1], v6, off
	v_or_b32_e32 v0, 0x4013000, v21
	v_or_b32_e32 v1, 0x13000, v21
	v_cndmask_b32_e64 v162, v1, v0, s[4:5]
	v_lshl_add_u64 v[6:7], v[18:19], 0, v[162:163]
	global_load_dword v6, v[6:7], off
	s_nop 0
	global_load_dword v1, v[4:5], off
	s_waitcnt vmcnt(0)
	v_fmac_f32_e32 v6, v11, v1
	v_mov_b32_e32 v1, v163
	v_lshl_add_u64 v[0:1], v[16:17], 0, v[0:1]
	global_store_dword v[0:1], v6, off
	v_or_b32_e32 v0, 0x4018000, v21
	v_or_b32_e32 v1, 0x18000, v21
	v_cndmask_b32_e64 v162, v1, v0, s[4:5]
	v_lshl_add_u64 v[6:7], v[18:19], 0, v[162:163]
	global_load_dword v6, v[6:7], off
	s_nop 0
	global_load_dword v1, v[2:3], off
	s_waitcnt vmcnt(0)
	v_fmac_f32_e32 v6, v12, v1
	v_mov_b32_e32 v1, v163
	v_lshl_add_u64 v[0:1], v[16:17], 0, v[0:1]
	global_store_dword v[0:1], v6, off
	v_or_b32_e32 v0, 0x4019000, v21
	v_or_b32_e32 v1, 0x19000, v21
	v_cndmask_b32_e64 v162, v1, v0, s[4:5]
	v_lshl_add_u64 v[2:3], v[18:19], 0, v[162:163]
	global_load_dword v2, v[2:3], off
	s_nop 0
	global_load_dword v1, v[4:5], off
	s_waitcnt vmcnt(0)
	v_fmac_f32_e32 v2, v13, v1
	v_mov_b32_e32 v1, v163
	v_lshl_add_u64 v[0:1], v[16:17], 0, v[0:1]
	global_store_dword v[0:1], v2, off
	v_or_b32_e32 v0, 0x401a000, v21
	v_or_b32_e32 v1, 0x1a000, v21
	v_cndmask_b32_e64 v162, v1, v0, s[4:5]
	v_lshl_add_u64 v[2:3], v[18:19], 0, v[162:163]
	global_load_dword v2, v[2:3], off
	s_nop 0
	global_load_dword v1, v[4:5], off
	s_waitcnt vmcnt(0)
	v_fmac_f32_e32 v2, v14, v1
	v_mov_b32_e32 v1, v163
	v_lshl_add_u64 v[0:1], v[16:17], 0, v[0:1]
	global_store_dword v[0:1], v2, off
	v_or_b32_e32 v0, 0x401b000, v21
	v_or_b32_e32 v1, 0x1b000, v21
	v_cndmask_b32_e64 v162, v1, v0, s[4:5]
	v_lshl_add_u64 v[2:3], v[18:19], 0, v[162:163]
	global_load_dword v2, v[2:3], off
	s_nop 0
	global_load_dword v1, v[4:5], off
	s_waitcnt vmcnt(0)
	v_fmac_f32_e32 v2, v15, v1
	v_mov_b32_e32 v1, v163
	v_lshl_add_u64 v[0:1], v[16:17], 0, v[0:1]
	global_store_dword v[0:1], v2, off

; DI void transpose_tile(const float* __restrict__ src, int K, int N, u16* __restrict__ dst, int kt, int nt, int mode, unsigned char* smem) {
;     ...
;   __syncthreads();
; #pragma unroll 4
;   for (int i = 0; i < 16; i++) { int k = i * 4 + ty; int n = n0 + tx; tile[k * 65 + tx] = (n < N) ? src[(size_t)(k0 + k) * N + n] : 0.f; }
;   __syncthreads();
.LBB0_1526:
	v_mov_b32_e32 v32, 0
	v_mov_b32_e32 v33, 0
	v_mov_b32_e32 v34, 0
	v_mov_b32_e32 v35, 0
	v_mov_b32_e32 v36, 0
	v_mov_b32_e32 v37, 0
	v_mov_b32_e32 v38, 0
	v_mov_b32_e32 v39, 0
	v_mov_b32_e32 v40, 0
	v_mov_b32_e32 v41, 0
	v_mov_b32_e32 v42, 0
	v_mov_b32_e32 v43, 0
	v_mov_b32_e32 v44, 0
	v_mov_b32_e32 v45, 0
	v_mov_b32_e32 v46, 0
	v_mov_b32_e32 v47, 0
	s_and_saveexec_b64 s[6:7], vcc
	s_cbranch_execz .Lmy_tr7_ld_done
	v_lshl_add_u64 v[16:17], v[6:7], 0, s[2:3]
	global_load_dword v32, v[16:17], off
	v_lshl_add_u64 v[16:17], v[4:5], 0, s[2:3]
	global_load_dword v33, v[16:17], off
	v_lshl_add_u64 v[16:17], v[2:3], 0, s[2:3]
	global_load_dword v34, v[16:17], off
	v_lshl_add_u64 v[16:17], v[0:1], 0, s[2:3]
	global_load_dword v35, v[16:17], off
	s_add_u32 s2, s2, 0x84800
	s_addc_u32 s3, s3, 0
	v_lshl_add_u64 v[16:17], v[6:7], 0, s[2:3]
	global_load_dword v36, v[16:17], off
	v_lshl_add_u64 v[16:17], v[4:5], 0, s[2:3]
	global_load_dword v37, v[16:17], off
	v_lshl_add_u64 v[16:17], v[2:3], 0, s[2:3]
	global_load_dword v38, v[16:17], off
	v_lshl_add_u64 v[16:17], v[0:1], 0, s[2:3]
	global_load_dword v39, v[16:17], off
	s_add_u32 s2, s2, 0x84800
	s_addc_u32 s3, s3, 0
	v_lshl_add_u64 v[16:17], v[6:7], 0, s[2:3]
	global_load_dword v40, v[16:17], off
	v_lshl_add_u64 v[16:17], v[4:5], 0, s[2:3]
	global_load_dword v41, v[16:17], off
	v_lshl_add_u64 v[16:17], v[2:3], 0, s[2:3]
	global_load_dword v42, v[16:17], off
	v_lshl_add_u64 v[16:17], v[0:1], 0, s[2:3]
	global_load_dword v43, v[16:17], off
	s_add_u32 s2, s2, 0x84800
	s_addc_u32 s3, s3, 0
	v_lshl_add_u64 v[16:17], v[6:7], 0, s[2:3]
	global_load_dword v44, v[16:17], off
	v_lshl_add_u64 v[16:17], v[4:5], 0, s[2:3]
	global_load_dword v45, v[16:17], off
	v_lshl_add_u64 v[16:17], v[2:3], 0, s[2:3]
	global_load_dword v46, v[16:17], off
	v_lshl_add_u64 v[16:17], v[0:1], 0, s[2:3]
	global_load_dword v47, v[16:17], off
.Lmy_tr7_ld_done:
	s_or_b64 exec, exec, s[6:7]
	s_waitcnt vmcnt(0)
	ds_write_b32 v13, v32
	ds_write_b32 v13, v33 offset:1040
	ds_write_b32 v13, v34 offset:2080
	ds_write_b32 v13, v35 offset:3120
	ds_write_b32 v13, v36 offset:4160
	ds_write_b32 v13, v37 offset:5200
	ds_write_b32 v13, v38 offset:6240
	ds_write_b32 v13, v39 offset:7280
	ds_write_b32 v13, v40 offset:8320
	ds_write_b32 v13, v41 offset:9360
	ds_write_b32 v13, v42 offset:10400
	ds_write_b32 v13, v43 offset:11440
	ds_write_b32 v13, v44 offset:12480
	ds_write_b32 v13, v45 offset:13520
	ds_write_b32 v13, v46 offset:14560
	ds_write_b32 v13, v47 offset:15600
	s_branch .LBB0_1534
